# v8 + SSD decay-mask computation: all LDS reads of the 32 elements issued up front, one wait, branch-light math (same arithmetic)
# speedup vs baseline: 1.0058x; 1.0014x over previous
; #define LAS __attribute__((address_space(3)))
; DI unsigned pk2(float lo, float hi) { f32x2 v = {lo, hi}; bf16x2_t b = __builtin_convertvector(v, bf16x2_t); return __builtin_bit_cast(unsigned, b); }
; DI void s3_ssd_unit(LAS unsigned char* lds, int tid, const ScanCtx& C, int b, int vc) {
;     ...
;             __syncthreads();
;             const int oct_ = tid & 7, tp_ = tid >> 3;
;             const u32x4 xr0 = *(const u32x4*)(Urow + h * 64 + (size_t)(2 * tp_) * UW + oct_ * 8), xr1 = *(const u32x4*)(Urow + h * 64 + (size_t)(2 * tp_ + 1) * UW + oct_ * 8);
;             const bf16* sfp = C.sts + ((size_t)(((b * NVC + vc) * 2 + 0) * 4 + h)) * 8192; const bf16* sbp = C.sts + ((size_t)(((b * NVC + vc) * 2 + 1) * 4 + h)) * 8192;
;             u32x4 hfv[2], hbv[2];
; #pragma unroll
;             for (int i = 0; i < 2; ++i) { const int itn = tid + NTHREADS * i, octn = itn & 15, rn = itn >> 4; hfv[i] = *(const u32x4*)(sfp + rn * 128 + octn * 8); hbv[i] = *(const u32x4*)(sbp + rn * 128 + octn * 8); }
;             u32x2 zz[4];
; #pragma unroll
;             for (int g4 = 0; g4 < 4; ++g4) zz[g4] = *(const u32x2*)(C.P + (size_t)rowq * NIN + 1536 + h * 64 + pt * 32 + 8 * g4 + 4 * hi);
;             { const LAS float* acf = sc + (SC_ACF * 4 + h) * 128; const LAS float* acb = sc + (SC_ACB * 4 + h) * 128; const LAS float* d0 = sc + (SC_DT0 * 4 + h) * 128; const LAS float* d1 = sc + (SC_DT1 * 4 + h) * 128;
; #pragma unroll
;               for (int q = 0; q < 2; ++q) { const int id = 2 * wave + q, st = id & 3, tq = id >> 2; const int t = tq * 32 + r32; const float aft = acf[t], abt = acb[t];
; #pragma unroll
;                   for (int g4 = 0; g4 < 4; ++g4) { float mv[4];
; #pragma unroll
;                       for (int j = 0; j < 4; ++j) { const int s = st * 32 + 8 * g4 + 4 * hi + j;
;                           float f; if (s < t) f = __expf(aft - acf[s]) * d0[s]; else if (s > t) f = __expf(abt - acb[s]) * d1[s]; else f = d0[s] + d1[s];
;                           mv[j] = (q ? gacc1[4 * g4 + j] : gacc0[4 * g4 + j]) * f; }
;                       u32x2 w; w.x = pk2(mv[0], mv[1]); w.y = pk2(mv[2], mv[3]);
;                       *(LAS u32x2*)(BkM + t * TP + st * 32 + 8 * g4 + 4 * hi) = w; } } }
.LBB0_362:
	s_or_b32 vcc_lo, s78, s90
	v_readlane_b32 s8, v253, 6
	s_lshl_b32 s8, vcc_lo, 7
	s_add_u32 s72, s83, s8
	s_addc_u32 s73, s86, 0
	v_lshl_add_u64 v[32:33], s[72:73], 0, v[100:101]
	v_lshl_add_u64 v[34:35], s[72:73], 0, v[102:103]
	s_or_b32 s72, vcc_lo, s87
	s_ashr_i32 s73, s72, 31
	s_lshl_b64 s[78:79], s[72:73], 14
	s_or_b32 s72, s72, 4
	s_ashr_i32 s73, s72, 31
	s_lshl_b64 s[72:73], s[72:73], 14
	v_readlane_b32 s9, v253, 7
	v_lshl_add_u64 v[48:49], v[104:105], 0, s[78:79]
	v_lshl_add_u64 v[50:51], v[104:105], 0, s[72:73]
	v_lshl_add_u64 v[32:33], v[32:33], 0, v[146:147]
	v_lshl_add_u64 v[34:35], v[34:35], 0, v[146:147]
	v_lshl_add_u64 v[40:41], v[48:49], 0, v[108:109]
	v_lshl_add_u64 v[44:45], v[50:51], 0, v[108:109]
	v_lshl_add_u64 v[48:49], v[48:49], 0, v[110:111]
	v_lshl_add_u64 v[52:53], v[50:51], 0, v[110:111]
	v_lshl_add_u64 v[56:57], v[106:107], 0, s[8:9]
	s_barrier
	global_load_dwordx4 v[36:39], v[32:33], off
	s_nop 0
	global_load_dwordx4 v[32:35], v[34:35], off
	s_nop 0
	global_load_dwordx4 v[40:43], v[40:41], off
	s_nop 0
	global_load_dwordx4 v[44:47], v[44:45], off
	s_nop 0
	global_load_dwordx4 v[48:51], v[48:49], off
	s_nop 0
	global_load_dwordx4 v[52:55], v[52:53], off
	s_nop 0
	global_load_dwordx2 v[118:119], v[56:57], off offset:3072
	global_load_dwordx2 v[116:117], v[56:57], off offset:3088
	global_load_dwordx2 v[114:115], v[56:57], off offset:3104
	global_load_dwordx2 v[112:113], v[56:57], off offset:3120
	s_lshl_b32 s72, vcc_lo, 9
	s_add_i32 s91, s72, 0
	v_lshlrev_b32_e32 v56, 2, v123
	s_add_i32 vcc_hi, s91, 0x800
	v_add_u32_e32 v64, s91, v56
	v_add_u32_e32 v124, vcc_hi, v56
	ds_read_b32 v57, v64
	ds_read_b32 v56, v124
	v_readlane_b32 s13, v253, 11
	s_mov_b32 s13, s9
	v_readlane_b32 s10, v253, 8
	v_readlane_b32 s11, v253, 9
	v_readlane_b32 s12, v253, 10
	v_readlane_b32 s14, v253, 12
	v_readlane_b32 s15, v253, 13
	v_readlane_b32 s16, v253, 14
	v_readlane_b32 s17, v253, 15
	v_readlane_b32 s18, v253, 16
	v_readlane_b32 s19, v253, 17
	v_readlane_b32 s20, v253, 18
	v_readlane_b32 s21, v253, 19
	v_readlane_b32 s22, v253, 20
	v_readlane_b32 s23, v253, 21
	s_mov_b64 s[72:73], exec
	v_lshlrev_b32_e32 v68, 2, v134
	v_add_u32_e32 v69, vcc_hi, v68
	v_add_u32_e32 v68, s91, v68
	v_lshlrev_b32_e32 v70, 2, v135
	v_add_u32_e32 v71, vcc_hi, v70
	v_add_u32_e32 v70, s91, v70
	v_readlane_b32 s8, v254, 12
	v_readlane_b32 s9, v254, 13
	s_and_b64 s[78:79], s[6:7], s[8:9]
	s_and_b64 exec, s[72:73], s[78:79]
	s_cbranch_execz .Ls3m_r0_1
	s_waitcnt lgkmcnt(13)
	ds_read_b32 v167, v68 offset:4096
	ds_read_b32 v168, v68 offset:6144
.Ls3m_r0_1:
	s_andn2_b64 s[78:79], s[6:7], s[8:9]
	s_and_b64 exec, s[72:73], s[78:79]
	s_cbranch_execz .Ls3m_r0_2
	s_waitcnt lgkmcnt(13)
	ds_read_b32 v167, v69
	ds_read_b32 v168, v68 offset:6144
.Ls3m_r0_2:
	s_andn2_b64 exec, s[72:73], s[6:7]
	s_cbranch_execz .Ls3m_r0_3
	s_waitcnt lgkmcnt(13)
	ds_read_b32 v167, v68
	ds_read_b32 v168, v68 offset:4096
.Ls3m_r0_3:
	s_and_b64 s[78:79], s[30:31], s[6:7]
	s_and_b64 exec, s[72:73], s[78:79]
	s_cbranch_execz .Ls3m_r1_1
	s_waitcnt lgkmcnt(13)
	ds_read_b32 v169, v69 offset:4
	ds_read_b32 v170, v68 offset:6148
.Ls3m_r1_1:
	s_andn2_b64 s[78:79], s[30:31], s[6:7]
	s_and_b64 exec, s[72:73], s[78:79]
	s_cbranch_execz .Ls3m_r1_2
	s_waitcnt lgkmcnt(13)
	ds_read_b32 v169, v68 offset:4100
	ds_read_b32 v170, v68 offset:6148
.Ls3m_r1_2:
	s_andn2_b64 exec, s[72:73], s[30:31]
	s_cbranch_execz .Ls3m_r1_3
	s_waitcnt lgkmcnt(13)
	ds_read_b32 v169, v68 offset:4
	ds_read_b32 v170, v68 offset:4100
.Ls3m_r1_3:
	v_readlane_b32 s8, v254, 14
	v_readlane_b32 s9, v254, 15
	s_and_b64 s[78:79], s[40:41], s[8:9]
	s_and_b64 exec, s[72:73], s[78:79]
	s_cbranch_execz .Ls3m_r2_1
	s_waitcnt lgkmcnt(13)
	ds_read_b32 v171, v68 offset:4104
	ds_read_b32 v172, v68 offset:6152
.Ls3m_r2_1:
	s_andn2_b64 s[78:79], s[40:41], s[8:9]
	s_and_b64 exec, s[72:73], s[78:79]
	s_cbranch_execz .Ls3m_r2_2
	s_waitcnt lgkmcnt(13)
	ds_read_b32 v171, v69 offset:8
	ds_read_b32 v172, v68 offset:6152
.Ls3m_r2_2:
	s_andn2_b64 exec, s[72:73], s[40:41]
	s_cbranch_execz .Ls3m_r2_3
	s_waitcnt lgkmcnt(13)
	ds_read_b32 v171, v68 offset:8
	ds_read_b32 v172, v68 offset:4104
.Ls3m_r2_3:
	v_readlane_b32 s8, v254, 16
	v_readlane_b32 s9, v254, 17
	s_and_b64 s[78:79], s[48:49], s[8:9]
	s_and_b64 exec, s[72:73], s[78:79]
	s_cbranch_execz .Ls3m_r3_1
	s_waitcnt lgkmcnt(13)
	ds_read_b32 v173, v68 offset:4108
	ds_read_b32 v174, v68 offset:6156
.Ls3m_r3_1:
	s_andn2_b64 s[78:79], s[48:49], s[8:9]
	s_and_b64 exec, s[72:73], s[78:79]
	s_cbranch_execz .Ls3m_r3_2
	s_waitcnt lgkmcnt(13)
	ds_read_b32 v173, v69 offset:12
	ds_read_b32 v174, v68 offset:6156
.Ls3m_r3_2:
	s_andn2_b64 exec, s[72:73], s[48:49]
	s_cbranch_execz .Ls3m_r3_3
	s_waitcnt lgkmcnt(13)
	ds_read_b32 v173, v68 offset:12
	ds_read_b32 v174, v68 offset:4108
.Ls3m_r3_3:
	v_readlane_b32 s8, v254, 18
	v_readlane_b32 s9, v254, 19
	s_and_b64 s[78:79], s[56:57], s[8:9]
	s_and_b64 exec, s[72:73], s[78:79]
	s_cbranch_execz .Ls3m_r4_1
	s_waitcnt lgkmcnt(13)
	ds_read_b32 v175, v68 offset:4128
	ds_read_b32 v176, v68 offset:6176
.Ls3m_r4_1:
	s_andn2_b64 s[78:79], s[56:57], s[8:9]
	s_and_b64 exec, s[72:73], s[78:79]
	s_cbranch_execz .Ls3m_r4_2
	s_waitcnt lgkmcnt(13)
	ds_read_b32 v175, v69 offset:32
	ds_read_b32 v176, v68 offset:6176
.Ls3m_r4_2:
	s_andn2_b64 exec, s[72:73], s[56:57]
	s_cbranch_execz .Ls3m_r4_3
	s_waitcnt lgkmcnt(13)
	ds_read_b32 v175, v68 offset:32
	ds_read_b32 v176, v68 offset:4128
.Ls3m_r4_3:
	v_readlane_b32 s8, v254, 20
	v_readlane_b32 s9, v254, 21
	s_and_b64 s[78:79], s[24:25], s[8:9]
	s_and_b64 exec, s[72:73], s[78:79]
	s_cbranch_execz .Ls3m_r5_1
	s_waitcnt lgkmcnt(13)
	ds_read_b32 v177, v68 offset:4132
	ds_read_b32 v178, v68 offset:6180
; DI void s3_ssd_unit(LAS unsigned char* lds, int tid, const ScanCtx& C, int b, int vc) {
;     ...
;               for (int q = 0; q < 2; ++q) { const int id = 2 * wave + q, st = id & 3, tq = id >> 2; const int t = tq * 32 + r32; const float aft = acf[t], abt = acb[t];
; #pragma unroll
;                   for (int g4 = 0; g4 < 4; ++g4) { float mv[4];
; #pragma unroll
;                       for (int j = 0; j < 4; ++j) { const int s = st * 32 + 8 * g4 + 4 * hi + j;
;                           float f; if (s < t) f = __expf(aft - acf[s]) * d0[s]; else if (s > t) f = __expf(abt - acb[s]) * d1[s]; else f = d0[s] + d1[s];
;                           mv[j] = (q ? gacc1[4 * g4 + j] : gacc0[4 * g4 + j]) * f; }
.Ls3m_r5_1:
	s_andn2_b64 s[78:79], s[24:25], s[8:9]
	s_and_b64 exec, s[72:73], s[78:79]
	s_cbranch_execz .Ls3m_r5_2
	s_waitcnt lgkmcnt(13)
	ds_read_b32 v177, v69 offset:36
	ds_read_b32 v178, v68 offset:6180
.Ls3m_r5_2:
	s_andn2_b64 exec, s[72:73], s[24:25]
	s_cbranch_execz .Ls3m_r5_3
	s_waitcnt lgkmcnt(13)
	ds_read_b32 v177, v68 offset:36
	ds_read_b32 v178, v68 offset:4132
.Ls3m_r5_3:
	v_readlane_b32 s8, v254, 22
	v_readlane_b32 s9, v254, 23
	s_and_b64 s[78:79], s[28:29], s[8:9]
	s_and_b64 exec, s[72:73], s[78:79]
	s_cbranch_execz .Ls3m_r6_1
	s_waitcnt lgkmcnt(13)
	ds_read_b32 v179, v68 offset:4136
	ds_read_b32 v180, v68 offset:6184
.Ls3m_r6_1:
	s_andn2_b64 s[78:79], s[28:29], s[8:9]
	s_and_b64 exec, s[72:73], s[78:79]
	s_cbranch_execz .Ls3m_r6_2
	s_waitcnt lgkmcnt(13)
	ds_read_b32 v179, v69 offset:40
	ds_read_b32 v180, v68 offset:6184
.Ls3m_r6_2:
	s_andn2_b64 exec, s[72:73], s[28:29]
	s_cbranch_execz .Ls3m_r6_3
	s_waitcnt lgkmcnt(13)
	ds_read_b32 v179, v68 offset:40
	ds_read_b32 v180, v68 offset:4136
.Ls3m_r6_3:
	v_readlane_b32 s8, v254, 24
	v_readlane_b32 s9, v254, 25
	s_and_b64 s[78:79], s[34:35], s[8:9]
	s_and_b64 exec, s[72:73], s[78:79]
	s_cbranch_execz .Ls3m_r7_1
	s_waitcnt lgkmcnt(13)
	ds_read_b32 v181, v68 offset:4140
	ds_read_b32 v182, v68 offset:6188
.Ls3m_r7_1:
	s_andn2_b64 s[78:79], s[34:35], s[8:9]
	s_and_b64 exec, s[72:73], s[78:79]
	s_cbranch_execz .Ls3m_r7_2
	s_waitcnt lgkmcnt(13)
	ds_read_b32 v181, v69 offset:44
	ds_read_b32 v182, v68 offset:6188
.Ls3m_r7_2:
	s_andn2_b64 exec, s[72:73], s[34:35]
	s_cbranch_execz .Ls3m_r7_3
	s_waitcnt lgkmcnt(13)
	ds_read_b32 v181, v68 offset:44
	ds_read_b32 v182, v68 offset:4140
.Ls3m_r7_3:
	v_readlane_b32 s8, v254, 26
	v_readlane_b32 s9, v254, 27
	s_and_b64 s[78:79], s[38:39], s[8:9]
	s_and_b64 exec, s[72:73], s[78:79]
	s_cbranch_execz .Ls3m_r8_1
	s_waitcnt lgkmcnt(13)
	ds_read_b32 v183, v68 offset:4160
	ds_read_b32 v184, v68 offset:6208
.Ls3m_r8_1:
	s_andn2_b64 s[78:79], s[38:39], s[8:9]
	s_and_b64 exec, s[72:73], s[78:79]
	s_cbranch_execz .Ls3m_r8_2
	s_waitcnt lgkmcnt(13)
	ds_read_b32 v183, v69 offset:64
	ds_read_b32 v184, v68 offset:6208
.Ls3m_r8_2:
	s_andn2_b64 exec, s[72:73], s[38:39]
	s_cbranch_execz .Ls3m_r8_3
	s_waitcnt lgkmcnt(13)
	ds_read_b32 v183, v68 offset:64
	ds_read_b32 v184, v68 offset:4160
.Ls3m_r8_3:
	v_readlane_b32 s8, v254, 28
	v_readlane_b32 s9, v254, 29
	s_and_b64 s[78:79], s[42:43], s[8:9]
	s_and_b64 exec, s[72:73], s[78:79]
	s_cbranch_execz .Ls3m_r9_1
	s_waitcnt lgkmcnt(13)
	ds_read_b32 v185, v68 offset:4164
	ds_read_b32 v186, v68 offset:6212
.Ls3m_r9_1:
	s_andn2_b64 s[78:79], s[42:43], s[8:9]
	s_and_b64 exec, s[72:73], s[78:79]
	s_cbranch_execz .Ls3m_r9_2
	s_waitcnt lgkmcnt(13)
	ds_read_b32 v185, v69 offset:68
	ds_read_b32 v186, v68 offset:6212
.Ls3m_r9_2:
	s_andn2_b64 exec, s[72:73], s[42:43]
	s_cbranch_execz .Ls3m_r9_3
	s_waitcnt lgkmcnt(13)
	ds_read_b32 v185, v68 offset:68
	ds_read_b32 v186, v68 offset:4164
.Ls3m_r9_3:
	v_readlane_b32 s8, v254, 30
	v_readlane_b32 s9, v254, 31
	s_and_b64 s[78:79], s[46:47], s[8:9]
	s_and_b64 exec, s[72:73], s[78:79]
	s_cbranch_execz .Ls3m_r10_1
	s_waitcnt lgkmcnt(13)
	ds_read_b32 v187, v68 offset:4168
	ds_read_b32 v188, v68 offset:6216
.Ls3m_r10_1:
	s_andn2_b64 s[78:79], s[46:47], s[8:9]
	s_and_b64 exec, s[72:73], s[78:79]
	s_cbranch_execz .Ls3m_r10_2
	s_waitcnt lgkmcnt(13)
	ds_read_b32 v187, v69 offset:72
	ds_read_b32 v188, v68 offset:6216
.Ls3m_r10_2:
	s_andn2_b64 exec, s[72:73], s[46:47]
	s_cbranch_execz .Ls3m_r10_3
	s_waitcnt lgkmcnt(13)
	ds_read_b32 v187, v68 offset:72
	ds_read_b32 v188, v68 offset:4168
.Ls3m_r10_3:
	v_readlane_b32 s8, v254, 32
	v_readlane_b32 s9, v254, 33
	s_and_b64 s[78:79], s[50:51], s[8:9]
	s_and_b64 exec, s[72:73], s[78:79]
	s_cbranch_execz .Ls3m_r11_1
	s_waitcnt lgkmcnt(13)
	ds_read_b32 v189, v68 offset:4172
	ds_read_b32 v190, v68 offset:6220
.Ls3m_r11_1:
	s_andn2_b64 s[78:79], s[50:51], s[8:9]
	s_and_b64 exec, s[72:73], s[78:79]
	s_cbranch_execz .Ls3m_r11_2
	s_waitcnt lgkmcnt(13)
	ds_read_b32 v189, v69 offset:76
	ds_read_b32 v190, v68 offset:6220
.Ls3m_r11_2:
	s_andn2_b64 exec, s[72:73], s[50:51]
	s_cbranch_execz .Ls3m_r11_3
	s_waitcnt lgkmcnt(13)
	ds_read_b32 v189, v68 offset:76
	ds_read_b32 v190, v68 offset:4172
.Ls3m_r11_3:
	v_readlane_b32 s8, v254, 34
	v_readlane_b32 s9, v254, 35
	s_and_b64 s[78:79], s[54:55], s[8:9]
	s_and_b64 exec, s[72:73], s[78:79]
	s_cbranch_execz .Ls3m_r12_1
	s_waitcnt lgkmcnt(13)
	ds_read_b32 v191, v68 offset:4192
	ds_read_b32 v192, v68 offset:6240
.Ls3m_r12_1:
	s_andn2_b64 s[78:79], s[54:55], s[8:9]
	s_and_b64 exec, s[72:73], s[78:79]
	s_cbranch_execz .Ls3m_r12_2
	s_waitcnt lgkmcnt(13)
	ds_read_b32 v191, v69 offset:96
	ds_read_b32 v192, v68 offset:6240
.Ls3m_r12_2:
	s_andn2_b64 exec, s[72:73], s[54:55]
	s_cbranch_execz .Ls3m_r12_3
	s_waitcnt lgkmcnt(13)
	ds_read_b32 v191, v68 offset:96
	ds_read_b32 v192, v68 offset:4192
.Ls3m_r12_3:
	v_readlane_b32 s8, v254, 36
	v_readlane_b32 s9, v254, 37
	s_and_b64 s[78:79], s[58:59], s[8:9]
	s_and_b64 exec, s[72:73], s[78:79]
	s_cbranch_execz .Ls3m_r13_1
	s_waitcnt lgkmcnt(13)
	ds_read_b32 v193, v68 offset:4196
	ds_read_b32 v194, v68 offset:6244
.Ls3m_r13_1:
	s_andn2_b64 s[78:79], s[58:59], s[8:9]
	s_and_b64 exec, s[72:73], s[78:79]
	s_cbranch_execz .Ls3m_r13_2
	s_waitcnt lgkmcnt(13)
	ds_read_b32 v193, v69 offset:100
	ds_read_b32 v194, v68 offset:6244
.Ls3m_r13_2:
	s_andn2_b64 exec, s[72:73], s[58:59]
	s_cbranch_execz .Ls3m_r13_3
	s_waitcnt lgkmcnt(13)
	ds_read_b32 v193, v68 offset:100
	ds_read_b32 v194, v68 offset:4196
; #define LAS __attribute__((address_space(3)))
; DI unsigned pk2(float lo, float hi) { f32x2 v = {lo, hi}; bf16x2_t b = __builtin_convertvector(v, bf16x2_t); return __builtin_bit_cast(unsigned, b); }
; DI void s3_ssd_unit(LAS unsigned char* lds, int tid, const ScanCtx& C, int b, int vc) {
;     ...
;             { const LAS float* acf = sc + (SC_ACF * 4 + h) * 128; const LAS float* acb = sc + (SC_ACB * 4 + h) * 128; const LAS float* d0 = sc + (SC_DT0 * 4 + h) * 128; const LAS float* d1 = sc + (SC_DT1 * 4 + h) * 128;
; #pragma unroll
;               for (int q = 0; q < 2; ++q) { const int id = 2 * wave + q, st = id & 3, tq = id >> 2; const int t = tq * 32 + r32; const float aft = acf[t], abt = acb[t];
; #pragma unroll
;                   for (int g4 = 0; g4 < 4; ++g4) { float mv[4];
; #pragma unroll
;                       for (int j = 0; j < 4; ++j) { const int s = st * 32 + 8 * g4 + 4 * hi + j;
;                           float f; if (s < t) f = __expf(aft - acf[s]) * d0[s]; else if (s > t) f = __expf(abt - acb[s]) * d1[s]; else f = d0[s] + d1[s];
;                           mv[j] = (q ? gacc1[4 * g4 + j] : gacc0[4 * g4 + j]) * f; }
;                       u32x2 w; w.x = pk2(mv[0], mv[1]); w.y = pk2(mv[2], mv[3]);
;                       *(LAS u32x2*)(BkM + t * TP + st * 32 + 8 * g4 + 4 * hi) = w; } } }
.Ls3m_r13_3:
	v_readlane_b32 s8, v254, 38
	v_readlane_b32 s9, v254, 39
	s_and_b64 s[78:79], s[62:63], s[8:9]
	s_and_b64 exec, s[72:73], s[78:79]
	s_cbranch_execz .Ls3m_r14_1
	s_waitcnt lgkmcnt(13)
	ds_read_b32 v195, v68 offset:4200
	ds_read_b32 v196, v68 offset:6248
.Ls3m_r14_1:
	s_andn2_b64 s[78:79], s[62:63], s[8:9]
	s_and_b64 exec, s[72:73], s[78:79]
	s_cbranch_execz .Ls3m_r14_2
	s_waitcnt lgkmcnt(13)
	ds_read_b32 v195, v69 offset:104
	ds_read_b32 v196, v68 offset:6248
.Ls3m_r14_2:
	s_andn2_b64 exec, s[72:73], s[62:63]
	s_cbranch_execz .Ls3m_r14_3
	s_waitcnt lgkmcnt(13)
	ds_read_b32 v195, v68 offset:104
	ds_read_b32 v196, v68 offset:4200
.Ls3m_r14_3:
	v_readlane_b32 s8, v254, 40
	v_readlane_b32 s9, v254, 41
	s_and_b64 s[78:79], s[66:67], s[8:9]
	s_and_b64 exec, s[72:73], s[78:79]
	s_cbranch_execz .Ls3m_r15_1
	s_waitcnt lgkmcnt(13)
	ds_read_b32 v197, v68 offset:4204
	ds_read_b32 v198, v68 offset:6252
.Ls3m_r15_1:
	s_andn2_b64 s[78:79], s[66:67], s[8:9]
	s_and_b64 exec, s[72:73], s[78:79]
	s_cbranch_execz .Ls3m_r15_2
	s_waitcnt lgkmcnt(13)
	ds_read_b32 v197, v69 offset:108
	ds_read_b32 v198, v68 offset:6252
.Ls3m_r15_2:
	s_andn2_b64 exec, s[72:73], s[66:67]
	s_cbranch_execz .Ls3m_r15_3
	s_waitcnt lgkmcnt(13)
	ds_read_b32 v197, v68 offset:108
	ds_read_b32 v198, v68 offset:4204
.Ls3m_r15_3:
	v_readlane_b32 s8, v254, 42
	v_readlane_b32 s9, v254, 43
	s_and_b64 s[78:79], s[70:71], s[8:9]
	s_and_b64 exec, s[72:73], s[78:79]
	s_cbranch_execz .Ls3m_r16_1
	s_waitcnt lgkmcnt(13)
	ds_read_b32 v199, v70 offset:4096
	ds_read_b32 v200, v70 offset:6144
.Ls3m_r16_1:
	s_andn2_b64 s[78:79], s[70:71], s[8:9]
	s_and_b64 exec, s[72:73], s[78:79]
	s_cbranch_execz .Ls3m_r16_2
	s_waitcnt lgkmcnt(13)
	ds_read_b32 v199, v71
	ds_read_b32 v200, v70 offset:6144
.Ls3m_r16_2:
	s_andn2_b64 exec, s[72:73], s[70:71]
	s_cbranch_execz .Ls3m_r16_3
	s_waitcnt lgkmcnt(13)
	ds_read_b32 v199, v70
	ds_read_b32 v200, v70 offset:4096
.Ls3m_r16_3:
	s_and_b64 s[78:79], s[74:75], s[70:71]
	s_and_b64 exec, s[72:73], s[78:79]
	s_cbranch_execz .Ls3m_r17_1
	s_waitcnt lgkmcnt(13)
	ds_read_b32 v201, v71 offset:4
	ds_read_b32 v202, v70 offset:6148
.Ls3m_r17_1:
	s_andn2_b64 s[78:79], s[74:75], s[70:71]
	s_and_b64 exec, s[72:73], s[78:79]
	s_cbranch_execz .Ls3m_r17_2
	s_waitcnt lgkmcnt(13)
	ds_read_b32 v201, v70 offset:4100
	ds_read_b32 v202, v70 offset:6148
.Ls3m_r17_2:
	s_andn2_b64 exec, s[72:73], s[74:75]
	s_cbranch_execz .Ls3m_r17_3
	s_waitcnt lgkmcnt(13)
	ds_read_b32 v201, v70 offset:4
	ds_read_b32 v202, v70 offset:4100
.Ls3m_r17_3:
	v_readlane_b32 s8, v254, 44
	v_readlane_b32 s9, v254, 45
	s_and_b64 s[78:79], s[76:77], s[8:9]
	s_and_b64 exec, s[72:73], s[78:79]
	s_cbranch_execz .Ls3m_r18_1
	s_waitcnt lgkmcnt(13)
	ds_read_b32 v203, v70 offset:4104
	ds_read_b32 v204, v70 offset:6152
.Ls3m_r18_1:
	s_andn2_b64 s[78:79], s[76:77], s[8:9]
	s_and_b64 exec, s[72:73], s[78:79]
	s_cbranch_execz .Ls3m_r18_2
	s_waitcnt lgkmcnt(13)
	ds_read_b32 v203, v71 offset:8
	ds_read_b32 v204, v70 offset:6152
.Ls3m_r18_2:
	s_andn2_b64 exec, s[72:73], s[76:77]
	s_cbranch_execz .Ls3m_r18_3
	s_waitcnt lgkmcnt(13)
	ds_read_b32 v203, v70 offset:8
	ds_read_b32 v204, v70 offset:4104
.Ls3m_r18_3:
	v_readlane_b32 s8, v254, 46
	v_readlane_b32 s9, v254, 47
	s_and_b64 s[78:79], s[80:81], s[8:9]
	s_and_b64 exec, s[72:73], s[78:79]
	s_cbranch_execz .Ls3m_r19_1
	s_waitcnt lgkmcnt(13)
	ds_read_b32 v205, v70 offset:4108
	ds_read_b32 v206, v70 offset:6156
.Ls3m_r19_1:
	s_andn2_b64 s[78:79], s[80:81], s[8:9]
	s_and_b64 exec, s[72:73], s[78:79]
	s_cbranch_execz .Ls3m_r19_2
	s_waitcnt lgkmcnt(13)
	ds_read_b32 v205, v71 offset:12
	ds_read_b32 v206, v70 offset:6156
.Ls3m_r19_2:
	s_andn2_b64 exec, s[72:73], s[80:81]
	s_cbranch_execz .Ls3m_r19_3
	s_waitcnt lgkmcnt(13)
	ds_read_b32 v205, v70 offset:12
	ds_read_b32 v206, v70 offset:4108
.Ls3m_r19_3:
	v_readlane_b32 s8, v254, 48
	v_readlane_b32 s9, v254, 49
	s_and_b64 s[78:79], s[84:85], s[8:9]
	s_and_b64 exec, s[72:73], s[78:79]
	s_cbranch_execz .Ls3m_r20_1
	s_waitcnt lgkmcnt(13)
	ds_read_b32 v218, v70 offset:4128
	ds_read_b32 v219, v70 offset:6176
.Ls3m_r20_1:
	s_andn2_b64 s[78:79], s[84:85], s[8:9]
	s_and_b64 exec, s[72:73], s[78:79]
	s_cbranch_execz .Ls3m_r20_2
	s_waitcnt lgkmcnt(13)
	ds_read_b32 v218, v71 offset:32
	ds_read_b32 v219, v70 offset:6176
.Ls3m_r20_2:
	s_andn2_b64 exec, s[72:73], s[84:85]
	s_cbranch_execz .Ls3m_r20_3
	s_waitcnt lgkmcnt(13)
	ds_read_b32 v218, v70 offset:32
	ds_read_b32 v219, v70 offset:4128
.Ls3m_r20_3:
	v_readlane_b32 s8, v254, 50
	v_readlane_b32 s9, v254, 51
	s_and_b64 s[78:79], s[88:89], s[8:9]
	s_and_b64 exec, s[72:73], s[78:79]
	s_cbranch_execz .Ls3m_r21_1
	s_waitcnt lgkmcnt(13)
	ds_read_b32 v220, v70 offset:4132
	ds_read_b32 v221, v70 offset:6180
.Ls3m_r21_1:
	s_andn2_b64 s[78:79], s[88:89], s[8:9]
	s_and_b64 exec, s[72:73], s[78:79]
	s_cbranch_execz .Ls3m_r21_2
	s_waitcnt lgkmcnt(13)
	ds_read_b32 v220, v71 offset:36
	ds_read_b32 v221, v70 offset:6180
.Ls3m_r21_2:
	s_andn2_b64 exec, s[72:73], s[88:89]
	s_cbranch_execz .Ls3m_r21_3
	s_waitcnt lgkmcnt(13)
	ds_read_b32 v220, v70 offset:36
	ds_read_b32 v221, v70 offset:4132
.Ls3m_r21_3:
	v_readlane_b32 s8, v254, 52
	v_readlane_b32 s9, v254, 53
	s_and_b64 s[78:79], s[92:93], s[8:9]
	s_and_b64 exec, s[72:73], s[78:79]
	s_cbranch_execz .Ls3m_r22_1
	s_waitcnt lgkmcnt(13)
	ds_read_b32 v222, v70 offset:4136
	ds_read_b32 v223, v70 offset:6184
.Ls3m_r22_1:
	s_andn2_b64 s[78:79], s[92:93], s[8:9]
	s_and_b64 exec, s[72:73], s[78:79]
	s_cbranch_execz .Ls3m_r22_2
	s_waitcnt lgkmcnt(13)
	ds_read_b32 v222, v71 offset:40
	ds_read_b32 v223, v70 offset:6184
; #define LAS __attribute__((address_space(3)))
; DI unsigned pk2(float lo, float hi) { f32x2 v = {lo, hi}; bf16x2_t b = __builtin_convertvector(v, bf16x2_t); return __builtin_bit_cast(unsigned, b); }
; DI void s3_ssd_unit(LAS unsigned char* lds, int tid, const ScanCtx& C, int b, int vc) {
;     ...
;             { const LAS float* acf = sc + (SC_ACF * 4 + h) * 128; const LAS float* acb = sc + (SC_ACB * 4 + h) * 128; const LAS float* d0 = sc + (SC_DT0 * 4 + h) * 128; const LAS float* d1 = sc + (SC_DT1 * 4 + h) * 128;
; #pragma unroll
;               for (int q = 0; q < 2; ++q) { const int id = 2 * wave + q, st = id & 3, tq = id >> 2; const int t = tq * 32 + r32; const float aft = acf[t], abt = acb[t];
; #pragma unroll
;                   for (int g4 = 0; g4 < 4; ++g4) { float mv[4];
; #pragma unroll
;                       for (int j = 0; j < 4; ++j) { const int s = st * 32 + 8 * g4 + 4 * hi + j;
;                           float f; if (s < t) f = __expf(aft - acf[s]) * d0[s]; else if (s > t) f = __expf(abt - acb[s]) * d1[s]; else f = d0[s] + d1[s];
;                           mv[j] = (q ? gacc1[4 * g4 + j] : gacc0[4 * g4 + j]) * f; }
;                       u32x2 w; w.x = pk2(mv[0], mv[1]); w.y = pk2(mv[2], mv[3]);
;                       *(LAS u32x2*)(BkM + t * TP + st * 32 + 8 * g4 + 4 * hi) = w; } } }
.Ls3m_r22_2:
	s_andn2_b64 exec, s[72:73], s[92:93]
	s_cbranch_execz .Ls3m_r22_3
	s_waitcnt lgkmcnt(13)
	ds_read_b32 v222, v70 offset:40
	ds_read_b32 v223, v70 offset:4136
.Ls3m_r22_3:
	v_readlane_b32 s8, v254, 54
	v_readlane_b32 s9, v254, 55
	s_and_b64 s[78:79], s[96:97], s[8:9]
	s_and_b64 exec, s[72:73], s[78:79]
	s_cbranch_execz .Ls3m_r23_1
	s_waitcnt lgkmcnt(13)
	ds_read_b32 v224, v70 offset:4140
	ds_read_b32 v225, v70 offset:6188
.Ls3m_r23_1:
	s_andn2_b64 s[78:79], s[96:97], s[8:9]
	s_and_b64 exec, s[72:73], s[78:79]
	s_cbranch_execz .Ls3m_r23_2
	s_waitcnt lgkmcnt(13)
	ds_read_b32 v224, v71 offset:44
	ds_read_b32 v225, v70 offset:6188
.Ls3m_r23_2:
	s_andn2_b64 exec, s[72:73], s[96:97]
	s_cbranch_execz .Ls3m_r23_3
	s_waitcnt lgkmcnt(13)
	ds_read_b32 v224, v70 offset:44
	ds_read_b32 v225, v70 offset:4140
.Ls3m_r23_3:
	v_readlane_b32 s8, v254, 56
	v_readlane_b32 s9, v254, 57
	s_and_b64 s[78:79], s[68:69], s[8:9]
	s_and_b64 exec, s[72:73], s[78:79]
	s_cbranch_execz .Ls3m_r24_1
	s_waitcnt lgkmcnt(13)
	ds_read_b32 v226, v70 offset:4160
	ds_read_b32 v227, v70 offset:6208
.Ls3m_r24_1:
	s_andn2_b64 s[78:79], s[68:69], s[8:9]
	s_and_b64 exec, s[72:73], s[78:79]
	s_cbranch_execz .Ls3m_r24_2
	s_waitcnt lgkmcnt(13)
	ds_read_b32 v226, v71 offset:64
	ds_read_b32 v227, v70 offset:6208
.Ls3m_r24_2:
	s_andn2_b64 exec, s[72:73], s[68:69]
	s_cbranch_execz .Ls3m_r24_3
	s_waitcnt lgkmcnt(13)
	ds_read_b32 v226, v70 offset:64
	ds_read_b32 v227, v70 offset:4160
.Ls3m_r24_3:
	v_readlane_b32 s8, v254, 58
	v_readlane_b32 s9, v254, 59
	s_and_b64 s[78:79], s[0:1], s[8:9]
	s_and_b64 exec, s[72:73], s[78:79]
	s_cbranch_execz .Ls3m_r25_1
	s_waitcnt lgkmcnt(13)
	ds_read_b32 v228, v70 offset:4164
	ds_read_b32 v229, v70 offset:6212
.Ls3m_r25_1:
	s_andn2_b64 s[78:79], s[0:1], s[8:9]
	s_and_b64 exec, s[72:73], s[78:79]
	s_cbranch_execz .Ls3m_r25_2
	s_waitcnt lgkmcnt(13)
	ds_read_b32 v228, v71 offset:68
	ds_read_b32 v229, v70 offset:6212
.Ls3m_r25_2:
	s_andn2_b64 exec, s[72:73], s[0:1]
	s_cbranch_execz .Ls3m_r25_3
	s_waitcnt lgkmcnt(13)
	ds_read_b32 v228, v70 offset:68
	ds_read_b32 v229, v70 offset:4164
.Ls3m_r25_3:
	v_readlane_b32 s8, v254, 60
	v_readlane_b32 s9, v254, 61
	s_and_b64 s[78:79], s[4:5], s[8:9]
	s_and_b64 exec, s[72:73], s[78:79]
	s_cbranch_execz .Ls3m_r26_1
	s_waitcnt lgkmcnt(13)
	ds_read_b32 v230, v70 offset:4168
	ds_read_b32 v231, v70 offset:6216
.Ls3m_r26_1:
	s_andn2_b64 s[78:79], s[4:5], s[8:9]
	s_and_b64 exec, s[72:73], s[78:79]
	s_cbranch_execz .Ls3m_r26_2
	s_waitcnt lgkmcnt(13)
	ds_read_b32 v230, v71 offset:72
	ds_read_b32 v231, v70 offset:6216
.Ls3m_r26_2:
	s_andn2_b64 exec, s[72:73], s[4:5]
	s_cbranch_execz .Ls3m_r26_3
	s_waitcnt lgkmcnt(13)
	ds_read_b32 v230, v70 offset:72
	ds_read_b32 v231, v70 offset:4168
.Ls3m_r26_3:
	v_readlane_b32 s8, v254, 62
	v_readlane_b32 s9, v254, 63
	s_and_b64 s[78:79], s[26:27], s[8:9]
	s_and_b64 exec, s[72:73], s[78:79]
	s_cbranch_execz .Ls3m_r27_1
	s_waitcnt lgkmcnt(13)
	ds_read_b32 v232, v70 offset:4172
	ds_read_b32 v233, v70 offset:6220
.Ls3m_r27_1:
	s_andn2_b64 s[78:79], s[26:27], s[8:9]
	s_and_b64 exec, s[72:73], s[78:79]
	s_cbranch_execz .Ls3m_r27_2
	s_waitcnt lgkmcnt(13)
	ds_read_b32 v232, v71 offset:76
	ds_read_b32 v233, v70 offset:6220
.Ls3m_r27_2:
	s_andn2_b64 exec, s[72:73], s[26:27]
	s_cbranch_execz .Ls3m_r27_3
	s_waitcnt lgkmcnt(13)
	ds_read_b32 v232, v70 offset:76
	ds_read_b32 v233, v70 offset:4172
.Ls3m_r27_3:
	v_readlane_b32 s8, v255, 0
	v_readlane_b32 s9, v255, 1
	s_and_b64 s[78:79], s[36:37], s[8:9]
	s_and_b64 exec, s[72:73], s[78:79]
	s_cbranch_execz .Ls3m_r28_1
	s_waitcnt lgkmcnt(13)
	ds_read_b32 v234, v70 offset:4192
	ds_read_b32 v235, v70 offset:6240
.Ls3m_r28_1:
	s_andn2_b64 s[78:79], s[36:37], s[8:9]
	s_and_b64 exec, s[72:73], s[78:79]
	s_cbranch_execz .Ls3m_r28_2
	s_waitcnt lgkmcnt(13)
	ds_read_b32 v234, v71 offset:96
	ds_read_b32 v235, v70 offset:6240
.Ls3m_r28_2:
	s_andn2_b64 exec, s[72:73], s[36:37]
	s_cbranch_execz .Ls3m_r28_3
	s_waitcnt lgkmcnt(13)
	ds_read_b32 v234, v70 offset:96
	ds_read_b32 v235, v70 offset:4192
.Ls3m_r28_3:
	v_readlane_b32 s8, v255, 2
	v_readlane_b32 s9, v255, 3
	s_and_b64 s[78:79], s[44:45], s[8:9]
	s_and_b64 exec, s[72:73], s[78:79]
	s_cbranch_execz .Ls3m_r29_1
	s_waitcnt lgkmcnt(13)
	ds_read_b32 v236, v70 offset:4196
	ds_read_b32 v237, v70 offset:6244
.Ls3m_r29_1:
	s_andn2_b64 s[78:79], s[44:45], s[8:9]
	s_and_b64 exec, s[72:73], s[78:79]
	s_cbranch_execz .Ls3m_r29_2
	s_waitcnt lgkmcnt(13)
	ds_read_b32 v236, v71 offset:100
	ds_read_b32 v237, v70 offset:6244
.Ls3m_r29_2:
	s_andn2_b64 exec, s[72:73], s[44:45]
	s_cbranch_execz .Ls3m_r29_3
	s_waitcnt lgkmcnt(13)
	ds_read_b32 v236, v70 offset:100
	ds_read_b32 v237, v70 offset:4196
.Ls3m_r29_3:
	v_readlane_b32 s8, v255, 4
	v_readlane_b32 s9, v255, 5
	s_and_b64 s[78:79], s[52:53], s[8:9]
	s_and_b64 exec, s[72:73], s[78:79]
	s_cbranch_execz .Ls3m_r30_1
	s_waitcnt lgkmcnt(13)
	ds_read_b32 v238, v70 offset:4200
	ds_read_b32 v239, v70 offset:6248
.Ls3m_r30_1:
	s_andn2_b64 s[78:79], s[52:53], s[8:9]
	s_and_b64 exec, s[72:73], s[78:79]
	s_cbranch_execz .Ls3m_r30_2
	s_waitcnt lgkmcnt(13)
	ds_read_b32 v238, v71 offset:104
	ds_read_b32 v239, v70 offset:6248
.Ls3m_r30_2:
	s_andn2_b64 exec, s[72:73], s[52:53]
	s_cbranch_execz .Ls3m_r30_3
	s_waitcnt lgkmcnt(13)
	ds_read_b32 v238, v70 offset:104
	ds_read_b32 v239, v70 offset:4200
.Ls3m_r30_3:
	s_and_b64 s[78:79], s[60:61], s[64:65]
	s_and_b64 exec, s[72:73], s[78:79]
	s_cbranch_execz .Ls3m_r31_1
	s_waitcnt lgkmcnt(13)
	ds_read_b32 v240, v70 offset:4204
	ds_read_b32 v241, v70 offset:6252
; #define LAS __attribute__((address_space(3)))
; DI unsigned pk2(float lo, float hi) { f32x2 v = {lo, hi}; bf16x2_t b = __builtin_convertvector(v, bf16x2_t); return __builtin_bit_cast(unsigned, b); }
; DI void s3_ssd_unit(LAS unsigned char* lds, int tid, const ScanCtx& C, int b, int vc) {
;     ...
;             { const LAS float* acf = sc + (SC_ACF * 4 + h) * 128; const LAS float* acb = sc + (SC_ACB * 4 + h) * 128; const LAS float* d0 = sc + (SC_DT0 * 4 + h) * 128; const LAS float* d1 = sc + (SC_DT1 * 4 + h) * 128;
; #pragma unroll
;               for (int q = 0; q < 2; ++q) { const int id = 2 * wave + q, st = id & 3, tq = id >> 2; const int t = tq * 32 + r32; const float aft = acf[t], abt = acb[t];
; #pragma unroll
;                   for (int g4 = 0; g4 < 4; ++g4) { float mv[4];
; #pragma unroll
;                       for (int j = 0; j < 4; ++j) { const int s = st * 32 + 8 * g4 + 4 * hi + j;
;                           float f; if (s < t) f = __expf(aft - acf[s]) * d0[s]; else if (s > t) f = __expf(abt - acb[s]) * d1[s]; else f = d0[s] + d1[s];
;                           mv[j] = (q ? gacc1[4 * g4 + j] : gacc0[4 * g4 + j]) * f; }
;                       u32x2 w; w.x = pk2(mv[0], mv[1]); w.y = pk2(mv[2], mv[3]);
;                       *(LAS u32x2*)(BkM + t * TP + st * 32 + 8 * g4 + 4 * hi) = w; } } }
.Ls3m_r31_1:
	s_andn2_b64 s[78:79], s[60:61], s[64:65]
	s_and_b64 exec, s[72:73], s[78:79]
	s_cbranch_execz .Ls3m_r31_2
	s_waitcnt lgkmcnt(13)
	ds_read_b32 v240, v71 offset:108
	ds_read_b32 v241, v70 offset:6252
.Ls3m_r31_2:
	s_andn2_b64 exec, s[72:73], s[60:61]
	s_cbranch_execz .Ls3m_r31_3
	s_waitcnt lgkmcnt(13)
	ds_read_b32 v240, v70 offset:108
	ds_read_b32 v241, v70 offset:4204
.Ls3m_r31_3:
	s_mov_b64 exec, s[72:73]
	s_waitcnt lgkmcnt(0)
	v_readlane_b32 s8, v254, 12
	v_readlane_b32 s9, v254, 13
	s_and_b64 s[78:79], s[6:7], s[8:9]
	s_andn2_b64 exec, s[72:73], s[78:79]
	s_cbranch_execz .Ls3m_c0_1
	v_cndmask_b32_e64 v65, v57, v56, s[6:7]
	v_sub_f32_e32 v65, v65, v167
	v_mul_f32_e32 v65, 0x3fb8aa3b, v65
	v_exp_f32_e32 v65, v65
	s_nop 0
	v_mul_f32_e32 v58, v168, v65
.Ls3m_c0_1:
	s_and_b64 exec, s[72:73], s[78:79]
	s_cbranch_execz .Ls3m_c0_2
	v_add_f32_e32 v58, v167, v168
.Ls3m_c0_2:
	s_andn2_b64 s[78:79], s[30:31], s[6:7]
	s_andn2_b64 exec, s[72:73], s[78:79]
	s_cbranch_execz .Ls3m_c1_1
	v_cndmask_b32_e64 v65, v57, v56, s[30:31]
	v_sub_f32_e32 v65, v65, v169
	v_mul_f32_e32 v65, 0x3fb8aa3b, v65
	v_exp_f32_e32 v65, v65
	s_nop 0
	v_mul_f32_e32 v59, v170, v65
.Ls3m_c1_1:
	s_and_b64 exec, s[72:73], s[78:79]
	s_cbranch_execz .Ls3m_c1_2
	v_add_f32_e32 v59, v169, v170
.Ls3m_c1_2:
	v_readlane_b32 s8, v254, 14
	v_readlane_b32 s9, v254, 15
	s_and_b64 s[78:79], s[40:41], s[8:9]
	s_andn2_b64 exec, s[72:73], s[78:79]
	s_cbranch_execz .Ls3m_c2_1
	v_cndmask_b32_e64 v65, v57, v56, s[40:41]
	v_sub_f32_e32 v65, v65, v171
	v_mul_f32_e32 v65, 0x3fb8aa3b, v65
	v_exp_f32_e32 v65, v65
	s_nop 0
	v_mul_f32_e32 v60, v172, v65
.Ls3m_c2_1:
	s_and_b64 exec, s[72:73], s[78:79]
	s_cbranch_execz .Ls3m_c2_2
	v_add_f32_e32 v60, v171, v172
.Ls3m_c2_2:
	v_readlane_b32 s8, v254, 16
	v_readlane_b32 s9, v254, 17
	s_and_b64 s[78:79], s[48:49], s[8:9]
	s_andn2_b64 exec, s[72:73], s[78:79]
	s_cbranch_execz .Ls3m_c3_1
	v_cndmask_b32_e64 v65, v57, v56, s[48:49]
	v_sub_f32_e32 v65, v65, v173
	v_mul_f32_e32 v65, 0x3fb8aa3b, v65
	v_exp_f32_e32 v65, v65
	s_nop 0
	v_mul_f32_e32 v61, v174, v65
.Ls3m_c3_1:
	s_and_b64 exec, s[72:73], s[78:79]
	s_cbranch_execz .Ls3m_c3_2
	v_add_f32_e32 v61, v173, v174
.Ls3m_c3_2:
	s_mov_b64 exec, s[72:73]
	v_mul_f32_e32 v60, v2, v60
	v_mul_f32_e32 v58, v0, v58
	v_mul_f32_e32 v59, v1, v59
	v_mul_f32_e32 v61, v3, v61
	v_cvt_pk_bf16_f32 v58, v58, v59
	v_cvt_pk_bf16_f32 v59, v60, v61
	ds_write_b64 v142, v[58:59] offset:51200
	v_readlane_b32 s8, v254, 18
	v_readlane_b32 s9, v254, 19
	s_and_b64 s[78:79], s[56:57], s[8:9]
	s_andn2_b64 exec, s[72:73], s[78:79]
	s_cbranch_execz .Ls3m_c4_1
	v_cndmask_b32_e64 v65, v57, v56, s[56:57]
	v_sub_f32_e32 v65, v65, v175
	v_mul_f32_e32 v65, 0x3fb8aa3b, v65
	v_exp_f32_e32 v65, v65
	s_nop 0
	v_mul_f32_e32 v58, v176, v65
.Ls3m_c4_1:
	s_and_b64 exec, s[72:73], s[78:79]
	s_cbranch_execz .Ls3m_c4_2
	v_add_f32_e32 v58, v175, v176
.Ls3m_c4_2:
	v_readlane_b32 s8, v254, 20
	v_readlane_b32 s9, v254, 21
	s_and_b64 s[78:79], s[24:25], s[8:9]
	s_andn2_b64 exec, s[72:73], s[78:79]
	s_cbranch_execz .Ls3m_c5_1
	v_cndmask_b32_e64 v65, v57, v56, s[24:25]
	v_sub_f32_e32 v65, v65, v177
	v_mul_f32_e32 v65, 0x3fb8aa3b, v65
	v_exp_f32_e32 v65, v65
	s_nop 0
	v_mul_f32_e32 v59, v178, v65
.Ls3m_c5_1:
	s_and_b64 exec, s[72:73], s[78:79]
	s_cbranch_execz .Ls3m_c5_2
	v_add_f32_e32 v59, v177, v178
.Ls3m_c5_2:
	v_readlane_b32 s8, v254, 22
	v_readlane_b32 s9, v254, 23
	s_and_b64 s[78:79], s[28:29], s[8:9]
	s_andn2_b64 exec, s[72:73], s[78:79]
	s_cbranch_execz .Ls3m_c6_1
	v_cndmask_b32_e64 v65, v57, v56, s[28:29]
	v_sub_f32_e32 v65, v65, v179
	v_mul_f32_e32 v65, 0x3fb8aa3b, v65
	v_exp_f32_e32 v65, v65
	s_nop 0
	v_mul_f32_e32 v60, v180, v65
.Ls3m_c6_1:
	s_and_b64 exec, s[72:73], s[78:79]
	s_cbranch_execz .Ls3m_c6_2
	v_add_f32_e32 v60, v179, v180
.Ls3m_c6_2:
	v_readlane_b32 s8, v254, 24
	v_readlane_b32 s9, v254, 25
	s_and_b64 s[78:79], s[34:35], s[8:9]
	s_andn2_b64 exec, s[72:73], s[78:79]
	s_cbranch_execz .Ls3m_c7_1
	v_cndmask_b32_e64 v65, v57, v56, s[34:35]
	v_sub_f32_e32 v65, v65, v181
	v_mul_f32_e32 v65, 0x3fb8aa3b, v65
	v_exp_f32_e32 v65, v65
	s_nop 0
	v_mul_f32_e32 v61, v182, v65
.Ls3m_c7_1:
	s_and_b64 exec, s[72:73], s[78:79]
	s_cbranch_execz .Ls3m_c7_2
	v_add_f32_e32 v61, v181, v182
.Ls3m_c7_2:
	s_mov_b64 exec, s[72:73]
	v_mul_f32_e32 v60, v6, v60
	v_mul_f32_e32 v58, v4, v58
	v_mul_f32_e32 v59, v5, v59
	v_mul_f32_e32 v61, v7, v61
	v_cvt_pk_bf16_f32 v58, v58, v59
	v_cvt_pk_bf16_f32 v59, v60, v61
	ds_write_b64 v142, v[58:59] offset:51216
	v_readlane_b32 s8, v254, 26
	v_readlane_b32 s9, v254, 27
	s_and_b64 s[78:79], s[38:39], s[8:9]
	s_andn2_b64 exec, s[72:73], s[78:79]
	s_cbranch_execz .Ls3m_c8_1
	v_cndmask_b32_e64 v65, v57, v56, s[38:39]
	v_sub_f32_e32 v65, v65, v183
	v_mul_f32_e32 v65, 0x3fb8aa3b, v65
	v_exp_f32_e32 v65, v65
	s_nop 0
	v_mul_f32_e32 v58, v184, v65
.Ls3m_c8_1:
	s_and_b64 exec, s[72:73], s[78:79]
	s_cbranch_execz .Ls3m_c8_2
	v_add_f32_e32 v58, v183, v184
.Ls3m_c8_2:
	v_readlane_b32 s8, v254, 28
	v_readlane_b32 s9, v254, 29
	s_and_b64 s[78:79], s[42:43], s[8:9]
	s_andn2_b64 exec, s[72:73], s[78:79]
	s_cbranch_execz .Ls3m_c9_1
	v_cndmask_b32_e64 v65, v57, v56, s[42:43]
	v_sub_f32_e32 v65, v65, v185
	v_mul_f32_e32 v65, 0x3fb8aa3b, v65
	v_exp_f32_e32 v65, v65
	s_nop 0
	v_mul_f32_e32 v59, v186, v65
.Ls3m_c9_1:
	s_and_b64 exec, s[72:73], s[78:79]
	s_cbranch_execz .Ls3m_c9_2
	v_add_f32_e32 v59, v185, v186
.Ls3m_c9_2:
	v_readlane_b32 s8, v254, 30
	v_readlane_b32 s9, v254, 31
	s_and_b64 s[78:79], s[46:47], s[8:9]
	s_andn2_b64 exec, s[72:73], s[78:79]
	s_cbranch_execz .Ls3m_c10_1
	v_cndmask_b32_e64 v65, v57, v56, s[46:47]
	v_sub_f32_e32 v65, v65, v187
	v_mul_f32_e32 v65, 0x3fb8aa3b, v65
	v_exp_f32_e32 v65, v65
	s_nop 0
	v_mul_f32_e32 v60, v188, v65
; #define LAS __attribute__((address_space(3)))
; DI unsigned pk2(float lo, float hi) { f32x2 v = {lo, hi}; bf16x2_t b = __builtin_convertvector(v, bf16x2_t); return __builtin_bit_cast(unsigned, b); }
; DI void s3_ssd_unit(LAS unsigned char* lds, int tid, const ScanCtx& C, int b, int vc) {
;     ...
;             { const LAS float* acf = sc + (SC_ACF * 4 + h) * 128; const LAS float* acb = sc + (SC_ACB * 4 + h) * 128; const LAS float* d0 = sc + (SC_DT0 * 4 + h) * 128; const LAS float* d1 = sc + (SC_DT1 * 4 + h) * 128;
; #pragma unroll
;               for (int q = 0; q < 2; ++q) { const int id = 2 * wave + q, st = id & 3, tq = id >> 2; const int t = tq * 32 + r32; const float aft = acf[t], abt = acb[t];
; #pragma unroll
;                   for (int g4 = 0; g4 < 4; ++g4) { float mv[4];
; #pragma unroll
;                       for (int j = 0; j < 4; ++j) { const int s = st * 32 + 8 * g4 + 4 * hi + j;
;                           float f; if (s < t) f = __expf(aft - acf[s]) * d0[s]; else if (s > t) f = __expf(abt - acb[s]) * d1[s]; else f = d0[s] + d1[s];
;                           mv[j] = (q ? gacc1[4 * g4 + j] : gacc0[4 * g4 + j]) * f; }
;                       u32x2 w; w.x = pk2(mv[0], mv[1]); w.y = pk2(mv[2], mv[3]);
;                       *(LAS u32x2*)(BkM + t * TP + st * 32 + 8 * g4 + 4 * hi) = w; } } }
.Ls3m_c10_1:
	s_and_b64 exec, s[72:73], s[78:79]
	s_cbranch_execz .Ls3m_c10_2
	v_add_f32_e32 v60, v187, v188
.Ls3m_c10_2:
	v_readlane_b32 s8, v254, 32
	v_readlane_b32 s9, v254, 33
	s_and_b64 s[78:79], s[50:51], s[8:9]
	s_andn2_b64 exec, s[72:73], s[78:79]
	s_cbranch_execz .Ls3m_c11_1
	v_cndmask_b32_e64 v65, v57, v56, s[50:51]
	v_sub_f32_e32 v65, v65, v189
	v_mul_f32_e32 v65, 0x3fb8aa3b, v65
	v_exp_f32_e32 v65, v65
	s_nop 0
	v_mul_f32_e32 v61, v190, v65
.Ls3m_c11_1:
	s_and_b64 exec, s[72:73], s[78:79]
	s_cbranch_execz .Ls3m_c11_2
	v_add_f32_e32 v61, v189, v190
.Ls3m_c11_2:
	s_mov_b64 exec, s[72:73]
	v_mul_f32_e32 v60, v10, v60
	v_mul_f32_e32 v58, v8, v58
	v_mul_f32_e32 v59, v9, v59
	v_mul_f32_e32 v61, v11, v61
	v_cvt_pk_bf16_f32 v58, v58, v59
	v_cvt_pk_bf16_f32 v59, v60, v61
	ds_write_b64 v142, v[58:59] offset:51232
	v_readlane_b32 s8, v254, 34
	v_readlane_b32 s9, v254, 35
	s_and_b64 s[78:79], s[54:55], s[8:9]
	s_andn2_b64 exec, s[72:73], s[78:79]
	s_cbranch_execz .Ls3m_c12_1
	v_cndmask_b32_e64 v65, v57, v56, s[54:55]
	v_sub_f32_e32 v65, v65, v191
	v_mul_f32_e32 v65, 0x3fb8aa3b, v65
	v_exp_f32_e32 v65, v65
	s_nop 0
	v_mul_f32_e32 v58, v192, v65
.Ls3m_c12_1:
	s_and_b64 exec, s[72:73], s[78:79]
	s_cbranch_execz .Ls3m_c12_2
	v_add_f32_e32 v58, v191, v192
.Ls3m_c12_2:
	v_readlane_b32 s8, v254, 36
	v_readlane_b32 s9, v254, 37
	s_and_b64 s[78:79], s[58:59], s[8:9]
	s_andn2_b64 exec, s[72:73], s[78:79]
	s_cbranch_execz .Ls3m_c13_1
	v_cndmask_b32_e64 v65, v57, v56, s[58:59]
	v_sub_f32_e32 v65, v65, v193
	v_mul_f32_e32 v65, 0x3fb8aa3b, v65
	v_exp_f32_e32 v65, v65
	s_nop 0
	v_mul_f32_e32 v59, v194, v65
.Ls3m_c13_1:
	s_and_b64 exec, s[72:73], s[78:79]
	s_cbranch_execz .Ls3m_c13_2
	v_add_f32_e32 v59, v193, v194
.Ls3m_c13_2:
	v_readlane_b32 s8, v254, 38
	v_readlane_b32 s9, v254, 39
	s_and_b64 s[78:79], s[62:63], s[8:9]
	s_andn2_b64 exec, s[72:73], s[78:79]
	s_cbranch_execz .Ls3m_c14_1
	v_cndmask_b32_e64 v65, v57, v56, s[62:63]
	v_sub_f32_e32 v65, v65, v195
	v_mul_f32_e32 v65, 0x3fb8aa3b, v65
	v_exp_f32_e32 v65, v65
	s_nop 0
	v_mul_f32_e32 v60, v196, v65
.Ls3m_c14_1:
	s_and_b64 exec, s[72:73], s[78:79]
	s_cbranch_execz .Ls3m_c14_2
	v_add_f32_e32 v60, v195, v196
.Ls3m_c14_2:
	v_readlane_b32 s8, v254, 40
	v_readlane_b32 s9, v254, 41
	s_and_b64 s[78:79], s[66:67], s[8:9]
	s_andn2_b64 exec, s[72:73], s[78:79]
	s_cbranch_execz .Ls3m_c15_1
	v_cndmask_b32_e64 v65, v57, v56, s[66:67]
	v_sub_f32_e32 v65, v65, v197
	v_mul_f32_e32 v65, 0x3fb8aa3b, v65
	v_exp_f32_e32 v65, v65
	s_nop 0
	v_mul_f32_e32 v61, v198, v65
.Ls3m_c15_1:
	s_and_b64 exec, s[72:73], s[78:79]
	s_cbranch_execz .Ls3m_c15_2
	v_add_f32_e32 v61, v197, v198
.Ls3m_c15_2:
	s_mov_b64 exec, s[72:73]
	v_mul_f32_e32 v67, v14, v60
	v_mul_f32_e32 v66, v12, v58
	v_mul_f32_e32 v58, v13, v59
	v_mul_f32_e32 v59, v15, v61
	v_cvt_pk_bf16_f32 v66, v66, v58
	v_cvt_pk_bf16_f32 v67, v67, v59
	ds_write_b64 v142, v[66:67] offset:51248
	v_readlane_b32 s8, v254, 42
	v_readlane_b32 s9, v254, 43
	s_and_b64 s[78:79], s[70:71], s[8:9]
	s_andn2_b64 exec, s[72:73], s[78:79]
	s_cbranch_execz .Ls3m_c16_1
	v_cndmask_b32_e64 v65, v57, v56, s[70:71]
	v_sub_f32_e32 v65, v65, v199
	v_mul_f32_e32 v65, 0x3fb8aa3b, v65
	v_exp_f32_e32 v65, v65
	s_nop 0
	v_mul_f32_e32 v58, v200, v65
.Ls3m_c16_1:
	s_and_b64 exec, s[72:73], s[78:79]
	s_cbranch_execz .Ls3m_c16_2
	v_add_f32_e32 v58, v199, v200
.Ls3m_c16_2:
	s_andn2_b64 s[78:79], s[74:75], s[70:71]
	s_andn2_b64 exec, s[72:73], s[78:79]
	s_cbranch_execz .Ls3m_c17_1
	v_cndmask_b32_e64 v65, v57, v56, s[74:75]
	v_sub_f32_e32 v65, v65, v201
	v_mul_f32_e32 v65, 0x3fb8aa3b, v65
	v_exp_f32_e32 v65, v65
	s_nop 0
	v_mul_f32_e32 v59, v202, v65
.Ls3m_c17_1:
	s_and_b64 exec, s[72:73], s[78:79]
	s_cbranch_execz .Ls3m_c17_2
	v_add_f32_e32 v59, v201, v202
.Ls3m_c17_2:
	v_readlane_b32 s8, v254, 44
	v_readlane_b32 s9, v254, 45
	s_and_b64 s[78:79], s[76:77], s[8:9]
	s_andn2_b64 exec, s[72:73], s[78:79]
	s_cbranch_execz .Ls3m_c18_1
	v_cndmask_b32_e64 v65, v57, v56, s[76:77]
	v_sub_f32_e32 v65, v65, v203
	v_mul_f32_e32 v65, 0x3fb8aa3b, v65
	v_exp_f32_e32 v65, v65
	s_nop 0
	v_mul_f32_e32 v60, v204, v65
.Ls3m_c18_1:
	s_and_b64 exec, s[72:73], s[78:79]
	s_cbranch_execz .Ls3m_c18_2
	v_add_f32_e32 v60, v203, v204
.Ls3m_c18_2:
	v_readlane_b32 s8, v254, 46
	v_readlane_b32 s9, v254, 47
	s_and_b64 s[78:79], s[80:81], s[8:9]
	s_andn2_b64 exec, s[72:73], s[78:79]
	s_cbranch_execz .Ls3m_c19_1
	v_cndmask_b32_e64 v65, v57, v56, s[80:81]
	v_sub_f32_e32 v65, v65, v205
	v_mul_f32_e32 v65, 0x3fb8aa3b, v65
	v_exp_f32_e32 v65, v65
	s_nop 0
	v_mul_f32_e32 v61, v206, v65
.Ls3m_c19_1:
	s_and_b64 exec, s[72:73], s[78:79]
	s_cbranch_execz .Ls3m_c19_2
	v_add_f32_e32 v61, v205, v206
.Ls3m_c19_2:
	s_mov_b64 exec, s[72:73]
	v_mul_f32_e32 v60, v18, v60
	v_mul_f32_e32 v58, v16, v58
	v_mul_f32_e32 v59, v17, v59
	v_mul_f32_e32 v61, v19, v61
	v_cvt_pk_bf16_f32 v58, v58, v59
	v_cvt_pk_bf16_f32 v59, v60, v61
	ds_write_b64 v143, v[58:59] offset:51200
	v_readlane_b32 s8, v254, 48
	v_readlane_b32 s9, v254, 49
	s_and_b64 s[78:79], s[84:85], s[8:9]
	s_andn2_b64 exec, s[72:73], s[78:79]
	s_cbranch_execz .Ls3m_c20_1
	v_cndmask_b32_e64 v65, v57, v56, s[84:85]
	v_sub_f32_e32 v65, v65, v218
	v_mul_f32_e32 v65, 0x3fb8aa3b, v65
	v_exp_f32_e32 v65, v65
	s_nop 0
	v_mul_f32_e32 v58, v219, v65
.Ls3m_c20_1:
	s_and_b64 exec, s[72:73], s[78:79]
	s_cbranch_execz .Ls3m_c20_2
	v_add_f32_e32 v58, v218, v219
; #define LAS __attribute__((address_space(3)))
; DI unsigned pk2(float lo, float hi) { f32x2 v = {lo, hi}; bf16x2_t b = __builtin_convertvector(v, bf16x2_t); return __builtin_bit_cast(unsigned, b); }
; DI void s3_ssd_unit(LAS unsigned char* lds, int tid, const ScanCtx& C, int b, int vc) {
;     ...
;             { const LAS float* acf = sc + (SC_ACF * 4 + h) * 128; const LAS float* acb = sc + (SC_ACB * 4 + h) * 128; const LAS float* d0 = sc + (SC_DT0 * 4 + h) * 128; const LAS float* d1 = sc + (SC_DT1 * 4 + h) * 128;
; #pragma unroll
;               for (int q = 0; q < 2; ++q) { const int id = 2 * wave + q, st = id & 3, tq = id >> 2; const int t = tq * 32 + r32; const float aft = acf[t], abt = acb[t];
; #pragma unroll
;                   for (int g4 = 0; g4 < 4; ++g4) { float mv[4];
; #pragma unroll
;                       for (int j = 0; j < 4; ++j) { const int s = st * 32 + 8 * g4 + 4 * hi + j;
;                           float f; if (s < t) f = __expf(aft - acf[s]) * d0[s]; else if (s > t) f = __expf(abt - acb[s]) * d1[s]; else f = d0[s] + d1[s];
;                           mv[j] = (q ? gacc1[4 * g4 + j] : gacc0[4 * g4 + j]) * f; }
;                       u32x2 w; w.x = pk2(mv[0], mv[1]); w.y = pk2(mv[2], mv[3]);
;                       *(LAS u32x2*)(BkM + t * TP + st * 32 + 8 * g4 + 4 * hi) = w; } } }
.Ls3m_c20_2:
	v_readlane_b32 s8, v254, 50
	v_readlane_b32 s9, v254, 51
	s_and_b64 s[78:79], s[88:89], s[8:9]
	s_andn2_b64 exec, s[72:73], s[78:79]
	s_cbranch_execz .Ls3m_c21_1
	v_cndmask_b32_e64 v65, v57, v56, s[88:89]
	v_sub_f32_e32 v65, v65, v220
	v_mul_f32_e32 v65, 0x3fb8aa3b, v65
	v_exp_f32_e32 v65, v65
	s_nop 0
	v_mul_f32_e32 v59, v221, v65
.Ls3m_c21_1:
	s_and_b64 exec, s[72:73], s[78:79]
	s_cbranch_execz .Ls3m_c21_2
	v_add_f32_e32 v59, v220, v221
.Ls3m_c21_2:
	v_readlane_b32 s8, v254, 52
	v_readlane_b32 s9, v254, 53
	s_and_b64 s[78:79], s[92:93], s[8:9]
	s_andn2_b64 exec, s[72:73], s[78:79]
	s_cbranch_execz .Ls3m_c22_1
	v_cndmask_b32_e64 v65, v57, v56, s[92:93]
	v_sub_f32_e32 v65, v65, v222
	v_mul_f32_e32 v65, 0x3fb8aa3b, v65
	v_exp_f32_e32 v65, v65
	s_nop 0
	v_mul_f32_e32 v60, v223, v65
.Ls3m_c22_1:
	s_and_b64 exec, s[72:73], s[78:79]
	s_cbranch_execz .Ls3m_c22_2
	v_add_f32_e32 v60, v222, v223
.Ls3m_c22_2:
	v_readlane_b32 s8, v254, 54
	v_readlane_b32 s9, v254, 55
	s_and_b64 s[78:79], s[96:97], s[8:9]
	s_andn2_b64 exec, s[72:73], s[78:79]
	s_cbranch_execz .Ls3m_c23_1
	v_cndmask_b32_e64 v65, v57, v56, s[96:97]
	v_sub_f32_e32 v65, v65, v224
	v_mul_f32_e32 v65, 0x3fb8aa3b, v65
	v_exp_f32_e32 v65, v65
	s_nop 0
	v_mul_f32_e32 v61, v225, v65
.Ls3m_c23_1:
	s_and_b64 exec, s[72:73], s[78:79]
	s_cbranch_execz .Ls3m_c23_2
	v_add_f32_e32 v61, v224, v225
.Ls3m_c23_2:
	s_mov_b64 exec, s[72:73]
	v_mul_f32_e32 v60, v22, v60
	v_mul_f32_e32 v58, v20, v58
	v_mul_f32_e32 v59, v21, v59
	v_mul_f32_e32 v61, v23, v61
	v_cvt_pk_bf16_f32 v58, v58, v59
	v_cvt_pk_bf16_f32 v59, v60, v61
	ds_write_b64 v143, v[58:59] offset:51216
	v_readlane_b32 s8, v254, 56
	v_readlane_b32 s9, v254, 57
	s_and_b64 s[78:79], s[68:69], s[8:9]
	s_andn2_b64 exec, s[72:73], s[78:79]
	s_cbranch_execz .Ls3m_c24_1
	v_cndmask_b32_e64 v65, v57, v56, s[68:69]
	v_sub_f32_e32 v65, v65, v226
	v_mul_f32_e32 v65, 0x3fb8aa3b, v65
	v_exp_f32_e32 v65, v65
	s_nop 0
	v_mul_f32_e32 v58, v227, v65
.Ls3m_c24_1:
	s_and_b64 exec, s[72:73], s[78:79]
	s_cbranch_execz .Ls3m_c24_2
	v_add_f32_e32 v58, v226, v227
.Ls3m_c24_2:
	v_readlane_b32 s8, v254, 58
	v_readlane_b32 s9, v254, 59
	s_and_b64 s[78:79], s[0:1], s[8:9]
	s_andn2_b64 exec, s[72:73], s[78:79]
	s_cbranch_execz .Ls3m_c25_1
	v_cndmask_b32_e64 v65, v57, v56, s[0:1]
	v_sub_f32_e32 v65, v65, v228
	v_mul_f32_e32 v65, 0x3fb8aa3b, v65
	v_exp_f32_e32 v65, v65
	s_nop 0
	v_mul_f32_e32 v59, v229, v65
.Ls3m_c25_1:
	s_and_b64 exec, s[72:73], s[78:79]
	s_cbranch_execz .Ls3m_c25_2
	v_add_f32_e32 v59, v228, v229
.Ls3m_c25_2:
	v_readlane_b32 s8, v254, 60
	v_readlane_b32 s9, v254, 61
	s_and_b64 s[78:79], s[4:5], s[8:9]
	s_andn2_b64 exec, s[72:73], s[78:79]
	s_cbranch_execz .Ls3m_c26_1
	v_cndmask_b32_e64 v65, v57, v56, s[4:5]
	v_sub_f32_e32 v65, v65, v230
	v_mul_f32_e32 v65, 0x3fb8aa3b, v65
	v_exp_f32_e32 v65, v65
	s_nop 0
	v_mul_f32_e32 v60, v231, v65
.Ls3m_c26_1:
	s_and_b64 exec, s[72:73], s[78:79]
	s_cbranch_execz .Ls3m_c26_2
	v_add_f32_e32 v60, v230, v231
.Ls3m_c26_2:
	v_readlane_b32 s8, v254, 62
	v_readlane_b32 s9, v254, 63
	s_and_b64 s[78:79], s[26:27], s[8:9]
	s_andn2_b64 exec, s[72:73], s[78:79]
	s_cbranch_execz .Ls3m_c27_1
	v_cndmask_b32_e64 v65, v57, v56, s[26:27]
	v_sub_f32_e32 v65, v65, v232
	v_mul_f32_e32 v65, 0x3fb8aa3b, v65
	v_exp_f32_e32 v65, v65
	s_nop 0
	v_mul_f32_e32 v61, v233, v65
.Ls3m_c27_1:
	s_and_b64 exec, s[72:73], s[78:79]
	s_cbranch_execz .Ls3m_c27_2
	v_add_f32_e32 v61, v232, v233
.Ls3m_c27_2:
	s_mov_b64 exec, s[72:73]
	v_mul_f32_e32 v60, v26, v60
	v_mul_f32_e32 v58, v24, v58
	v_mul_f32_e32 v59, v25, v59
	v_mul_f32_e32 v61, v27, v61
	v_cvt_pk_bf16_f32 v58, v58, v59
	v_cvt_pk_bf16_f32 v59, v60, v61
	ds_write_b64 v143, v[58:59] offset:51232
	v_readlane_b32 s8, v255, 0
	v_readlane_b32 s9, v255, 1
	s_and_b64 s[78:79], s[36:37], s[8:9]
	s_andn2_b64 exec, s[72:73], s[78:79]
	s_cbranch_execz .Ls3m_c28_1
	v_cndmask_b32_e64 v65, v57, v56, s[36:37]
	v_sub_f32_e32 v65, v65, v234
	v_mul_f32_e32 v65, 0x3fb8aa3b, v65
	v_exp_f32_e32 v65, v65
	s_nop 0
	v_mul_f32_e32 v58, v235, v65
.Ls3m_c28_1:
	s_and_b64 exec, s[72:73], s[78:79]
	s_cbranch_execz .Ls3m_c28_2
	v_add_f32_e32 v58, v234, v235
.Ls3m_c28_2:
	v_readlane_b32 s8, v255, 2
	v_readlane_b32 s9, v255, 3
	s_and_b64 s[78:79], s[44:45], s[8:9]
	s_andn2_b64 exec, s[72:73], s[78:79]
	s_cbranch_execz .Ls3m_c29_1
	v_cndmask_b32_e64 v65, v57, v56, s[44:45]
	v_sub_f32_e32 v65, v65, v236
	v_mul_f32_e32 v65, 0x3fb8aa3b, v65
	v_exp_f32_e32 v65, v65
	s_nop 0
	v_mul_f32_e32 v59, v237, v65
.Ls3m_c29_1:
	s_and_b64 exec, s[72:73], s[78:79]
	s_cbranch_execz .Ls3m_c29_2
	v_add_f32_e32 v59, v236, v237
.Ls3m_c29_2:
	v_readlane_b32 s8, v255, 4
	v_readlane_b32 s9, v255, 5
	s_and_b64 s[78:79], s[52:53], s[8:9]
	s_andn2_b64 exec, s[72:73], s[78:79]
	s_cbranch_execz .Ls3m_c30_1
	v_cndmask_b32_e64 v65, v57, v56, s[52:53]
	v_sub_f32_e32 v65, v65, v238
	v_mul_f32_e32 v65, 0x3fb8aa3b, v65
	v_exp_f32_e32 v65, v65
	s_nop 0
	v_mul_f32_e32 v60, v239, v65
.Ls3m_c30_1:
	s_and_b64 exec, s[72:73], s[78:79]
	s_cbranch_execz .Ls3m_c30_2
	v_add_f32_e32 v60, v238, v239
.Ls3m_c30_2:
	s_and_b64 s[78:79], s[60:61], s[64:65]
	s_andn2_b64 exec, s[72:73], s[78:79]
	s_cbranch_execz .Ls3m_c31_1
	v_cndmask_b32_e64 v65, v57, v56, s[60:61]
	v_sub_f32_e32 v65, v65, v240
	v_mul_f32_e32 v65, 0x3fb8aa3b, v65
	v_exp_f32_e32 v65, v65
	s_nop 0
	v_mul_f32_e32 v61, v241, v65
.Ls3m_c31_1:
	s_and_b64 exec, s[72:73], s[78:79]
	s_cbranch_execz .Ls3m_c31_2
	v_add_f32_e32 v61, v240, v241
.Ls3m_c31_2:
	s_mov_b64 exec, s[72:73]
	s_mov_b32 s94, 0x9000
	s_movk_i32 s95, 0x2000
	s_mov_b64 s[72:73], exec
	s_lshl_b32 s79, vcc_lo, 6
	s_branch .LBB0_361
